# peer_q: wave priority 2 during the GEMM k-loop, 0 during top-k (so matrix/LDS/VMEM issue of co-resident workgroups is not queued behind top-k VALU)
# speedup vs baseline: 1.0045x; 1.0023x over previous
;   DI u16* hb() const { return (u16*)(ws + OFF_hb); }
; #define tid_opaque() tid_from(WAVE_S)
;   const int tid = tid_opaque(), lane = tid & 63;
;   u16* Xs = lds;
;   u16* Ys = lds + 128 * LSTR;
;   const int lr = tid >> 3, lc = (tid & 7) * 8;
;   const u16* xg = X + (size_t)lr * RS + lc;
;   const u16* yg = Y + (size_t)lr * RS + lc;
;   u32x4 xr[4], yr[4];
; #pragma unroll
;   for (int it = 0; it < 4; ++it) {
;     xr[it] = *(const u32x4*)(xg + (size_t)it * 32 * RS);
;     yr[it] = *(const u32x4*)(yg + (size_t)it * 32 * RS);
;   }
; #pragma unroll
;   for (int a = 0; a < TI; ++a)
; #pragma unroll
;     for (int b = 0; b < TJ; ++b)
; #pragma unroll
;       for (int r = 0; r < 16; ++r) acc[a][b][r] = 0.f;
;   const int fr = lane & 31, fh = (lane >> 5) * 8;
; DI void phase_peer_q(const Params& p, int layer, u16* lds, const int WAVE_S) {
;     ...
; #pragma unroll 1
;     for (int half = 0; half < 2; ++half) {
;       f32x16 acc[4][1];
;       gemm_tile<4, 1>(W + (size_t)(head * 2 + half) * 128 * DM, p.hb() + (size_t)tt * 128 * DM, acc, lds, 0, wave * 32, WAVE_S);
.Lpq_skipld:
	v_addc_co_u32_e32 v9, vcc, 0, v7, vcc
	v_add_co_u32_e32 v10, vcc, s81, v116
	v_and_b32_e32 v3, 31, v12
	s_nop 0
	v_addc_co_u32_e32 v11, vcc, 0, v117, vcc
	v_add_co_u32_e32 v8, vcc, s12, v6
	s_nop 0
	s_nop 0
	v_addc_co_u32_e32 v9, vcc, 0, v7, vcc
	v_add_co_u32_e32 v10, vcc, s12, v116
	s_add_i32 s28, s18, s19
	s_nop 0
	v_addc_co_u32_e32 v11, vcc, 0, v117, vcc
	v_add_co_u32_e32 v6, vcc, s86, v6
	v_addc_co_u32_e32 v7, vcc, 0, v7, vcc
	v_add_co_u32_e32 v8, vcc, s86, v116
	v_and_b32_e32 v0, 7, v12
	s_nop 0
	v_addc_co_u32_e32 v9, vcc, 0, v117, vcc
	v_lshrrev_b32_e32 v6, 1, v12
	v_and_b32_e32 v6, 16, v6
	v_or_b32_e32 v7, v3, v122
	s_nop 0
	s_lshl_b64 s[50:51], s[28:29], 1
	s_add_u32 s50, s96, s50
	v_mul_u32_u24_e32 v3, 0x90, v3
	v_lshl_or_b32 v4, v0, 4, v4
	s_addc_u32 s51, s97, s51
	v_mov_b32_e32 v2, 0
	s_nop 0
	s_mov_b64 s[50:51], s[44:45]
	s_nop 0
	v_mov_b32_e32 v3, v2
	v_mov_b32_e32 v4, v2
	v_mov_b32_e32 v5, v2
	v_mov_b32_e32 v6, v2
	v_mov_b32_e32 v7, v2
	v_mov_b32_e32 v8, v2
	v_mov_b32_e32 v9, v2
	v_mov_b32_e32 v10, v2
	v_mov_b32_e32 v11, v2
	v_mov_b32_e32 v12, v2
	v_mov_b32_e32 v13, v2
	v_mov_b32_e32 v14, v2
	v_mov_b32_e32 v15, v2
	v_mov_b32_e32 v16, v2
	v_mov_b32_e32 v17, v2
	v_mov_b32_e32 v18, v2
	v_mov_b32_e32 v19, v2
	v_mov_b32_e32 v20, v2
	v_mov_b32_e32 v21, v2
	v_mov_b32_e32 v22, v2
	v_mov_b32_e32 v23, v2
	v_mov_b32_e32 v24, v2
	v_mov_b32_e32 v25, v2
	v_mov_b32_e32 v26, v2
	v_mov_b32_e32 v27, v2
	v_mov_b32_e32 v28, v2
	v_mov_b32_e32 v29, v2
	v_mov_b32_e32 v30, v2
	v_mov_b32_e32 v31, v2
	v_mov_b32_e32 v32, v2
	v_mov_b32_e32 v33, v2
	s_waitcnt vmcnt(12)
	v_mov_b32_e32 v34, v2
	v_mov_b32_e32 v35, v2
	v_mov_b32_e32 v36, v2
	v_mov_b32_e32 v37, v2
	s_waitcnt vmcnt(8)
	v_mov_b32_e32 v38, v2
	v_mov_b32_e32 v39, v2
	v_mov_b32_e32 v40, v2
	v_mov_b32_e32 v41, v2
	v_mov_b32_e32 v42, v2
	v_mov_b32_e32 v43, v2
	v_mov_b32_e32 v44, v2
	v_mov_b32_e32 v45, v2
	v_mov_b32_e32 v46, v2
	v_mov_b32_e32 v47, v2
	v_mov_b32_e32 v48, v2
	v_mov_b32_e32 v49, v2
	v_mov_b32_e32 v50, v2
	v_mov_b32_e32 v51, v2
	v_mov_b32_e32 v52, v2
	v_mov_b32_e32 v53, v2
	s_waitcnt vmcnt(8)
	v_mov_b32_e32 v54, v2
	v_mov_b32_e32 v55, v2
	v_mov_b32_e32 v56, v2
	v_mov_b32_e32 v57, v2
	v_mov_b32_e32 v58, v2
	v_mov_b32_e32 v59, v2
	v_mov_b32_e32 v60, v2
	v_mov_b32_e32 v61, v2
	v_mov_b32_e32 v62, v2
	v_mov_b32_e32 v63, v2
	v_mov_b32_e32 v64, v2
	v_mov_b32_e32 v65, v2
	s_setprio 2
	s_movk_i32 s19, 7

; DI void phase_peer_q(const Params& p, int layer, u16* lds, const int WAVE_S) {
;     ...
; #pragma unroll
;       for (int i = 0; i < 16; ++i) t[i] = -3.0e38f;
; #pragma unroll
;       for (int nt = 0; nt < 4; ++nt)
; #pragma unroll
;         for (int i = 0; i < 16; ++i) {
;           const uint32_t n = nt * 32 + (i & 3) + 8 * (i >> 2) + 4 * h;
;           const float v = __uint_as_float((__float_as_uint(acc[nt][0][i]) & ~127u) | n);
;           ins16n(t, v, nt * 16 + i);
;         }
.Lpq_nopf:
	s_setprio 0
	s_nop 7
	s_nop 7
	s_andn2_b64 vcc, exec, s[48:49]
	v_and_or_b32 v50, v50, s88, v123
	v_or_b32_e32 v0, 1, v123
	v_and_or_b32 v51, v51, s88, v0
	v_or_b32_e32 v0, 2, v123
	v_and_or_b32 v52, v52, s88, v0
	v_or_b32_e32 v0, 3, v123
	v_and_or_b32 v53, v53, s88, v0
	v_or_b32_e32 v0, 8, v123
	v_and_or_b32 v54, v54, s88, v0
	v_or_b32_e32 v0, 9, v123
	v_and_or_b32 v55, v55, s88, v0
	v_or_b32_e32 v0, 10, v123
	v_and_or_b32 v56, v56, s88, v0
	v_or_b32_e32 v0, 11, v123
	v_and_or_b32 v57, v57, s88, v0
	v_or_b32_e32 v0, 16, v123
	v_and_or_b32 v58, v58, s88, v0
	v_or_b32_e32 v0, 17, v123
	v_and_or_b32 v59, v59, s88, v0
	v_or_b32_e32 v0, 18, v123
	v_and_or_b32 v60, v60, s88, v0
	v_or_b32_e32 v0, 19, v123
	v_and_or_b32 v61, v61, s88, v0
	v_or_b32_e32 v0, 24, v123
	v_and_or_b32 v62, v62, s88, v0
	v_or_b32_e32 v0, 25, v123
	v_and_or_b32 v63, v63, s88, v0
	v_or_b32_e32 v0, 26, v123
	v_and_or_b32 v64, v64, s88, v0
	v_or_b32_e32 v0, 27, v123
	v_and_or_b32 v65, v65, s88, v0
	v_or_b32_e32 v0, 32, v123
	v_and_or_b32 v34, v34, s88, v0
	v_or_b32_e32 v0, 33, v123
	v_and_or_b32 v35, v35, s88, v0
	v_or_b32_e32 v0, 34, v123
	v_and_or_b32 v36, v36, s88, v0
	v_or_b32_e32 v0, 35, v123
	v_and_or_b32 v37, v37, s88, v0
	v_or_b32_e32 v0, 40, v123
	v_and_or_b32 v38, v38, s88, v0
	v_or_b32_e32 v0, 41, v123
	v_and_or_b32 v39, v39, s88, v0
	v_or_b32_e32 v0, 42, v123
	v_and_or_b32 v40, v40, s88, v0
	v_or_b32_e32 v0, 43, v123
	v_and_or_b32 v41, v41, s88, v0
	v_or_b32_e32 v0, 48, v123
	v_and_or_b32 v42, v42, s88, v0
	v_or_b32_e32 v0, 49, v123
	v_and_or_b32 v43, v43, s88, v0
	v_or_b32_e32 v0, 50, v123
	v_and_or_b32 v44, v44, s88, v0
	v_or_b32_e32 v0, 51, v123
	v_and_or_b32 v45, v45, s88, v0
	v_or_b32_e32 v0, 56, v123
	v_and_or_b32 v46, v46, s88, v0
	v_or_b32_e32 v0, 57, v123
	v_and_or_b32 v47, v47, s88, v0
	v_or_b32_e32 v0, 58, v123
	v_and_or_b32 v48, v48, s88, v0
	v_or_b32_e32 v0, 59, v123
	v_and_or_b32 v49, v49, s88, v0
	v_or_b32_e32 v0, 64, v123
	v_and_or_b32 v18, v18, s88, v0
	v_or_b32_e32 v0, 65, v123
	v_and_or_b32 v19, v19, s88, v0
	v_or_b32_e32 v0, 66, v123
	v_and_or_b32 v20, v20, s88, v0
	v_or_b32_e32 v0, 67, v123
	v_and_or_b32 v21, v21, s88, v0
	v_or_b32_e32 v0, 72, v123
	v_and_or_b32 v22, v22, s88, v0
	v_or_b32_e32 v0, 73, v123
	v_and_or_b32 v23, v23, s88, v0
	v_or_b32_e32 v0, 74, v123
	v_and_or_b32 v24, v24, s88, v0
	v_or_b32_e32 v0, 75, v123
	v_and_or_b32 v25, v25, s88, v0
	v_or_b32_e32 v0, 80, v123
	v_and_or_b32 v26, v26, s88, v0
	v_or_b32_e32 v0, 81, v123
	v_and_or_b32 v27, v27, s88, v0
	v_or_b32_e32 v0, 82, v123
	v_and_or_b32 v28, v28, s88, v0
	v_or_b32_e32 v0, 83, v123
	v_and_or_b32 v29, v29, s88, v0
	v_or_b32_e32 v0, 88, v123
	v_and_or_b32 v30, v30, s88, v0
	v_or_b32_e32 v0, 89, v123
	v_and_or_b32 v31, v31, s88, v0
	v_or_b32_e32 v0, 90, v123
	v_and_or_b32 v32, v32, s88, v0
	v_or_b32_e32 v0, 91, v123
	v_and_or_b32 v33, v33, s88, v0
	v_or_b32_e32 v0, 96, v123
	v_and_or_b32 v2, v2, s88, v0
	v_or_b32_e32 v0, 97, v123
	v_and_or_b32 v3, v3, s88, v0
	v_or_b32_e32 v0, 98, v123
	v_and_or_b32 v4, v4, s88, v0
	v_or_b32_e32 v0, 99, v123
	v_and_or_b32 v5, v5, s88, v0
	v_or_b32_e32 v0, 104, v123
	v_and_or_b32 v6, v6, s88, v0
	v_or_b32_e32 v0, 105, v123
	v_and_or_b32 v7, v7, s88, v0
	v_or_b32_e32 v0, 106, v123
	v_and_or_b32 v8, v8, s88, v0
	v_or_b32_e32 v0, 107, v123
	v_and_or_b32 v9, v9, s88, v0
	v_and_or_b32 v10, v10, s88, v125
	v_and_or_b32 v11, v11, s88, v126
	v_and_or_b32 v12, v12, s88, v127
	v_and_or_b32 v13, v13, s88, v128
	v_and_or_b32 v14, v14, s88, v129
	v_and_or_b32 v15, v15, s88, v130
	v_and_or_b32 v16, v16, s88, v131
	v_and_or_b32 v17, v17, s88, v132
	v_min_f32_e32 v134, v2, v3
	v_max_f32_e32 v2, v2, v3
	v_min_f32_e32 v135, v4, v5
	v_max_f32_e32 v4, v4, v5
	v_min_f32_e32 v136, v2, v4
	v_max_f32_e32 v2, v2, v4
	v_min_f32_e32 v137, v134, v135
	v_max_f32_e32 v134, v134, v135
	v_min_f32_e32 v138, v134, v136
	v_max_f32_e32 v134, v134, v136
	v_min_f32_e32 v139, v6, v7
	v_max_f32_e32 v6, v6, v7
	v_min_f32_e32 v140, v8, v9
	v_max_f32_e32 v8, v8, v9
	v_min_f32_e32 v141, v6, v8
	v_max_f32_e32 v6, v6, v8
	v_min_f32_e32 v142, v139, v140
	v_max_f32_e32 v139, v139, v140
	v_min_f32_e32 v143, v139, v141
	v_max_f32_e32 v139, v139, v141
	v_min_f32_e32 v144, v2, v6
	v_max_f32_e32 v2, v2, v6
	v_min_f32_e32 v145, v138, v143
	v_max_f32_e32 v138, v138, v143
	v_min_f32_e32 v148, v138, v144
	v_max_f32_e32 v138, v138, v144
	v_min_f32_e32 v149, v134, v139
	v_max_f32_e32 v134, v134, v139
	v_min_f32_e32 v150, v137, v142
	v_max_f32_e32 v137, v137, v142
	v_min_f32_e32 v151, v137, v149
	v_max_f32_e32 v137, v137, v149
	v_min_f32_e32 v152, v134, v138
	v_max_f32_e32 v134, v134, v138
	v_min_f32_e32 v153, v137, v148
	v_max_f32_e32 v137, v137, v148
	v_min_f32_e32 v154, v151, v145
	v_max_f32_e32 v151, v151, v145
	v_min_f32_e32 v155, v10, v11
	v_max_f32_e32 v10, v10, v11
	v_min_f32_e32 v0, v12, v13
	v_max_f32_e32 v12, v12, v13
	v_min_f32_e32 v3, v10, v12
	v_max_f32_e32 v10, v10, v12
	v_min_f32_e32 v5, v155, v0
	v_max_f32_e32 v155, v155, v0
	v_min_f32_e32 v4, v155, v3
	v_max_f32_e32 v155, v155, v3
	v_min_f32_e32 v135, v14, v15
	v_max_f32_e32 v14, v14, v15
	v_min_f32_e32 v136, v16, v17
	v_max_f32_e32 v16, v16, v17
	v_min_f32_e32 v7, v14, v16
	v_max_f32_e32 v14, v14, v16
	v_min_f32_e32 v9, v135, v136
	v_max_f32_e32 v135, v135, v136
	v_min_f32_e32 v8, v135, v7
	v_max_f32_e32 v135, v135, v7
	v_min_f32_e32 v140, v10, v14
	v_max_f32_e32 v10, v10, v14
	v_min_f32_e32 v141, v4, v8
	v_max_f32_e32 v4, v4, v8
	v_min_f32_e32 v6, v4, v140
	v_max_f32_e32 v4, v4, v140
	v_min_f32_e32 v143, v155, v135
	v_max_f32_e32 v155, v155, v135
	v_min_f32_e32 v144, v5, v9
	v_max_f32_e32 v5, v5, v9
; DI void phase_peer_q(const Params& p, int layer, u16* lds, const int WAVE_S) {
;     ...
; #pragma unroll
;       for (int i = 0; i < 16; ++i) t[i] = -3.0e38f;
; #pragma unroll
;       for (int nt = 0; nt < 4; ++nt)
; #pragma unroll
;         for (int i = 0; i < 16; ++i) {
;           const uint32_t n = nt * 32 + (i & 3) + 8 * (i >> 2) + 4 * h;
;           const float v = __uint_as_float((__float_as_uint(acc[nt][0][i]) & ~127u) | n);
;           ins16n(t, v, nt * 16 + i);
;         }
	v_min_f32_e32 v139, v5, v143
	v_max_f32_e32 v5, v5, v143
	v_min_f32_e32 v142, v155, v4
	v_max_f32_e32 v155, v155, v4
	v_min_f32_e32 v149, v5, v6
	v_max_f32_e32 v5, v5, v6
	v_min_f32_e32 v138, v139, v141
	v_max_f32_e32 v139, v139, v141
	v_min_f32_e32 v148, v2, v10
	v_max_f32_e32 v2, v2, v10
	v_min_f32_e32 v145, v153, v149
	v_max_f32_e32 v153, v153, v149
	v_min_f32_e32 v11, v153, v148
	v_max_f32_e32 v153, v153, v148
	v_min_f32_e32 v13, v152, v142
	v_max_f32_e32 v152, v152, v142
	v_min_f32_e32 v12, v154, v138
	v_max_f32_e32 v154, v154, v138
	v_min_f32_e32 v0, v154, v13
	v_max_f32_e32 v154, v154, v13
	v_min_f32_e32 v3, v152, v153
	v_max_f32_e32 v152, v152, v153
	v_min_f32_e32 v15, v154, v11
	v_max_f32_e32 v154, v154, v11
	v_min_f32_e32 v17, v0, v145
	v_max_f32_e32 v0, v0, v145
	v_min_f32_e32 v16, v134, v155
	v_max_f32_e32 v134, v134, v155
	v_min_f32_e32 v136, v151, v139
	v_max_f32_e32 v151, v151, v139
	v_min_f32_e32 v7, v151, v16
	v_max_f32_e32 v151, v151, v16
	v_min_f32_e32 v14, v137, v5
	v_max_f32_e32 v137, v137, v5
	v_min_f32_e32 v8, v150, v144
	v_max_f32_e32 v150, v150, v144
	v_min_f32_e32 v140, v150, v14
	v_max_f32_e32 v150, v150, v14
	v_min_f32_e32 v135, v137, v151
	v_max_f32_e32 v137, v137, v151
	v_min_f32_e32 v9, v150, v7
	v_max_f32_e32 v150, v150, v7
	v_min_f32_e32 v143, v140, v136
	v_max_f32_e32 v140, v140, v136
	v_min_f32_e32 v4, v134, v152
	v_max_f32_e32 v134, v134, v152
	v_min_f32_e32 v6, v137, v3
	v_max_f32_e32 v137, v137, v3
	v_min_f32_e32 v141, v135, v154
	v_max_f32_e32 v135, v135, v154
	v_min_f32_e32 v10, v150, v15
	v_max_f32_e32 v150, v150, v15
	v_min_f32_e32 v149, v9, v0
	v_max_f32_e32 v9, v9, v0
	v_min_f32_e32 v148, v140, v17
	v_max_f32_e32 v140, v140, v17
	v_min_f32_e32 v142, v143, v12
	v_max_f32_e32 v143, v143, v12
	v_min_f32_e32 v138, v18, v19
	v_max_f32_e32 v18, v18, v19
	v_min_f32_e32 v13, v20, v21
	v_max_f32_e32 v20, v20, v21
	v_min_f32_e32 v153, v18, v20
	v_max_f32_e32 v18, v18, v20
	v_min_f32_e32 v11, v138, v13
	v_max_f32_e32 v138, v138, v13
	v_min_f32_e32 v145, v138, v153
	v_max_f32_e32 v138, v138, v153
	v_min_f32_e32 v155, v22, v23
	v_max_f32_e32 v22, v22, v23
	v_min_f32_e32 v139, v24, v25
	v_max_f32_e32 v24, v24, v25
	v_min_f32_e32 v16, v22, v24
	v_max_f32_e32 v22, v22, v24
	v_min_f32_e32 v5, v155, v139
	v_max_f32_e32 v155, v155, v139
	v_min_f32_e32 v144, v155, v16
	v_max_f32_e32 v155, v155, v16
	v_min_f32_e32 v14, v18, v22
	v_max_f32_e32 v18, v18, v22
	v_min_f32_e32 v151, v145, v144
	v_max_f32_e32 v145, v145, v144
	v_min_f32_e32 v7, v145, v14
	v_max_f32_e32 v145, v145, v14
	v_min_f32_e32 v136, v138, v155
	v_max_f32_e32 v138, v138, v155
	v_min_f32_e32 v152, v11, v5
	v_max_f32_e32 v11, v11, v5
	v_min_f32_e32 v3, v11, v136
	v_max_f32_e32 v11, v11, v136
	v_min_f32_e32 v154, v138, v145
	v_max_f32_e32 v138, v138, v145
	v_min_f32_e32 v15, v11, v7
	v_max_f32_e32 v11, v11, v7
	v_min_f32_e32 v0, v3, v151
	v_max_f32_e32 v3, v3, v151
	v_min_f32_e32 v17, v26, v27
	v_max_f32_e32 v26, v26, v27
	v_min_f32_e32 v12, v28, v29
	v_max_f32_e32 v28, v28, v29
	v_min_f32_e32 v19, v26, v28
	v_max_f32_e32 v26, v26, v28
	v_min_f32_e32 v21, v17, v12
	v_max_f32_e32 v17, v17, v12
	v_min_f32_e32 v20, v17, v19
	v_max_f32_e32 v17, v17, v19
	v_min_f32_e32 v13, v30, v31
	v_max_f32_e32 v30, v30, v31
	v_min_f32_e32 v153, v32, v33
	v_max_f32_e32 v32, v32, v33
	v_min_f32_e32 v23, v30, v32
	v_max_f32_e32 v30, v30, v32
	v_min_f32_e32 v25, v13, v153
	v_max_f32_e32 v13, v13, v153
	v_min_f32_e32 v24, v13, v23
	v_max_f32_e32 v13, v13, v23
	v_min_f32_e32 v139, v26, v30
	v_max_f32_e32 v26, v26, v30
	v_min_f32_e32 v16, v20, v24
	v_max_f32_e32 v20, v20, v24
	v_min_f32_e32 v22, v20, v139
	v_max_f32_e32 v20, v20, v139
	v_min_f32_e32 v144, v17, v13
	v_max_f32_e32 v17, v17, v13
	v_min_f32_e32 v14, v21, v25
	v_max_f32_e32 v21, v21, v25
	v_min_f32_e32 v155, v21, v144
	v_max_f32_e32 v21, v21, v144
	v_min_f32_e32 v5, v17, v20
	v_max_f32_e32 v17, v17, v20
	v_min_f32_e32 v136, v21, v22
	v_max_f32_e32 v21, v21, v22
	v_min_f32_e32 v145, v155, v16
	v_max_f32_e32 v155, v155, v16
	v_min_f32_e32 v7, v18, v26
	v_max_f32_e32 v18, v18, v26
	v_min_f32_e32 v151, v15, v136
	v_max_f32_e32 v15, v15, v136
	v_min_f32_e32 v27, v15, v7
	v_max_f32_e32 v15, v15, v7
	v_min_f32_e32 v29, v154, v5
	v_max_f32_e32 v154, v154, v5
	v_min_f32_e32 v28, v0, v145
	v_max_f32_e32 v0, v0, v145
	v_min_f32_e32 v12, v0, v29
	v_max_f32_e32 v0, v0, v29
	v_min_f32_e32 v19, v154, v15
	v_max_f32_e32 v154, v154, v15
	v_min_f32_e32 v31, v0, v27
	v_max_f32_e32 v0, v0, v27
	v_min_f32_e32 v33, v12, v151
	v_max_f32_e32 v12, v12, v151
	v_min_f32_e32 v32, v138, v17
	v_max_f32_e32 v138, v138, v17
	v_min_f32_e32 v153, v3, v155
	v_max_f32_e32 v3, v3, v155
	v_min_f32_e32 v23, v3, v32
	v_max_f32_e32 v3, v3, v32
	v_min_f32_e32 v30, v11, v21
	v_max_f32_e32 v11, v11, v21
	v_min_f32_e32 v24, v152, v14
	v_max_f32_e32 v152, v152, v14
	v_min_f32_e32 v139, v152, v30
	v_max_f32_e32 v152, v152, v30
	v_min_f32_e32 v13, v11, v3
	v_max_f32_e32 v11, v11, v3
	v_min_f32_e32 v25, v152, v23
	v_max_f32_e32 v152, v152, v23
	v_min_f32_e32 v144, v139, v153
	v_max_f32_e32 v139, v139, v153
	v_min_f32_e32 v20, v138, v154
	v_max_f32_e32 v138, v138, v154
	v_min_f32_e32 v22, v11, v19
	v_max_f32_e32 v11, v11, v19
	v_min_f32_e32 v16, v13, v0
	v_max_f32_e32 v13, v13, v0
	v_min_f32_e32 v26, v152, v31
	v_max_f32_e32 v152, v152, v31
	v_min_f32_e32 v136, v25, v12
	v_max_f32_e32 v25, v25, v12
	v_min_f32_e32 v7, v139, v33
	v_max_f32_e32 v139, v139, v33
	v_min_f32_e32 v5, v144, v28
	v_max_f32_e32 v144, v144, v28
	v_min_f32_e32 v145, v34, v35
	v_max_f32_e32 v34, v34, v35
	v_min_f32_e32 v29, v36, v37
	v_max_f32_e32 v36, v36, v37
	v_min_f32_e32 v15, v34, v36
; DI void ins16n(float (&t)[16], float x, int nf) {
; #pragma unroll
;   for (int i = 15; i >= 1; --i)
;     if (i <= nf) t[i] = __builtin_amdgcn_fmed3f(t[i - 1], t[i], x);
;   t[0] = fmaxf(t[0], x);
; }
; DI void phase_peer_q(const Params& p, int layer, u16* lds, const int WAVE_S) {
;     ...
; #pragma unroll
;       for (int i = 0; i < 16; ++i) t[i] = -3.0e38f;
; #pragma unroll
;       for (int nt = 0; nt < 4; ++nt)
; #pragma unroll
;         for (int i = 0; i < 16; ++i) {
;           const uint32_t n = nt * 32 + (i & 3) + 8 * (i >> 2) + 4 * h;
;           const float v = __uint_as_float((__float_as_uint(acc[nt][0][i]) & ~127u) | n);
;           ins16n(t, v, nt * 16 + i);
;         }
	v_max_f32_e32 v34, v34, v36
	v_min_f32_e32 v27, v145, v29
	v_max_f32_e32 v145, v145, v29
	v_min_f32_e32 v151, v145, v15
	v_max_f32_e32 v145, v145, v15
	v_min_f32_e32 v17, v38, v39
	v_max_f32_e32 v38, v38, v39
	v_min_f32_e32 v155, v40, v41
	v_max_f32_e32 v40, v40, v41
	v_min_f32_e32 v32, v38, v40
	v_max_f32_e32 v38, v38, v40
	v_min_f32_e32 v21, v17, v155
	v_max_f32_e32 v17, v17, v155
	v_min_f32_e32 v14, v17, v32
	v_max_f32_e32 v17, v17, v32
	v_min_f32_e32 v30, v34, v38
	v_max_f32_e32 v34, v34, v38
	v_min_f32_e32 v3, v151, v14
	v_max_f32_e32 v151, v151, v14
	v_min_f32_e32 v23, v151, v30
	v_max_f32_e32 v151, v151, v30
	v_min_f32_e32 v153, v145, v17
	v_max_f32_e32 v145, v145, v17
	v_min_f32_e32 v154, v27, v21
	v_max_f32_e32 v27, v27, v21
	v_min_f32_e32 v19, v27, v153
	v_max_f32_e32 v27, v27, v153
	v_min_f32_e32 v0, v145, v151
	v_max_f32_e32 v145, v145, v151
	v_min_f32_e32 v31, v27, v23
	v_max_f32_e32 v27, v27, v23
	v_min_f32_e32 v12, v19, v3
	v_max_f32_e32 v19, v19, v3
	v_min_f32_e32 v33, v42, v43
	v_max_f32_e32 v42, v42, v43
	v_min_f32_e32 v28, v44, v45
	v_max_f32_e32 v44, v44, v45
	v_min_f32_e32 v35, v42, v44
	v_max_f32_e32 v42, v42, v44
	v_min_f32_e32 v37, v33, v28
	v_max_f32_e32 v33, v33, v28
	v_min_f32_e32 v36, v33, v35
	v_max_f32_e32 v33, v33, v35
	v_min_f32_e32 v29, v46, v47
	v_max_f32_e32 v46, v46, v47
	v_min_f32_e32 v15, v48, v49
	v_max_f32_e32 v48, v48, v49
	v_min_f32_e32 v39, v46, v48
	v_max_f32_e32 v46, v46, v48
	v_min_f32_e32 v41, v29, v15
	v_max_f32_e32 v29, v29, v15
	v_min_f32_e32 v40, v29, v39
	v_max_f32_e32 v29, v29, v39
	v_min_f32_e32 v155, v42, v46
	v_max_f32_e32 v42, v42, v46
	v_min_f32_e32 v32, v36, v40
	v_max_f32_e32 v36, v36, v40
	v_min_f32_e32 v38, v36, v155
	v_max_f32_e32 v36, v36, v155
	v_min_f32_e32 v14, v33, v29
	v_max_f32_e32 v33, v33, v29
	v_min_f32_e32 v30, v37, v41
	v_max_f32_e32 v37, v37, v41
	v_min_f32_e32 v17, v37, v14
	v_max_f32_e32 v37, v37, v14
	v_min_f32_e32 v21, v33, v36
	v_max_f32_e32 v33, v33, v36
	v_min_f32_e32 v153, v37, v38
	v_max_f32_e32 v37, v37, v38
	v_min_f32_e32 v151, v17, v32
	v_max_f32_e32 v17, v17, v32
	v_min_f32_e32 v23, v34, v42
	v_max_f32_e32 v34, v34, v42
	v_min_f32_e32 v3, v31, v153
	v_max_f32_e32 v31, v31, v153
	v_min_f32_e32 v43, v31, v23
	v_max_f32_e32 v31, v31, v23
	v_min_f32_e32 v45, v0, v21
	v_max_f32_e32 v0, v0, v21
	v_min_f32_e32 v44, v12, v151
	v_max_f32_e32 v12, v12, v151
	v_min_f32_e32 v28, v12, v45
	v_max_f32_e32 v12, v12, v45
	v_min_f32_e32 v35, v0, v31
	v_max_f32_e32 v0, v0, v31
	v_min_f32_e32 v47, v12, v43
	v_max_f32_e32 v12, v12, v43
	v_min_f32_e32 v49, v28, v3
	v_max_f32_e32 v28, v28, v3
	v_min_f32_e32 v48, v145, v33
	v_max_f32_e32 v145, v145, v33
	v_min_f32_e32 v15, v19, v17
	v_max_f32_e32 v19, v19, v17
	v_min_f32_e32 v39, v19, v48
	v_max_f32_e32 v19, v19, v48
	v_min_f32_e32 v46, v27, v37
	v_max_f32_e32 v27, v27, v37
	v_min_f32_e32 v40, v154, v30
	v_max_f32_e32 v154, v154, v30
	v_min_f32_e32 v155, v154, v46
	v_max_f32_e32 v154, v154, v46
	v_min_f32_e32 v29, v27, v19
	v_max_f32_e32 v27, v27, v19
	v_min_f32_e32 v41, v154, v39
	v_max_f32_e32 v154, v154, v39
	v_min_f32_e32 v14, v155, v15
	v_max_f32_e32 v155, v155, v15
	v_min_f32_e32 v36, v145, v0
	v_max_f32_e32 v145, v145, v0
	v_min_f32_e32 v38, v27, v35
	v_max_f32_e32 v27, v27, v35
	v_min_f32_e32 v32, v29, v12
	v_max_f32_e32 v29, v29, v12
	v_min_f32_e32 v42, v154, v47
	v_max_f32_e32 v154, v154, v47
	v_min_f32_e32 v153, v41, v28
	v_max_f32_e32 v41, v41, v28
	v_min_f32_e32 v23, v155, v49
	v_max_f32_e32 v155, v155, v49
	v_min_f32_e32 v21, v14, v44
	v_max_f32_e32 v14, v14, v44
	v_min_f32_e32 v151, v50, v51
	v_max_f32_e32 v50, v50, v51
	v_min_f32_e32 v45, v52, v53
	v_max_f32_e32 v52, v52, v53
	v_min_f32_e32 v31, v50, v52
	v_max_f32_e32 v50, v50, v52
	v_min_f32_e32 v43, v151, v45
	v_max_f32_e32 v151, v151, v45
	v_min_f32_e32 v3, v151, v31
	v_max_f32_e32 v151, v151, v31
	v_min_f32_e32 v33, v54, v55
	v_max_f32_e32 v54, v54, v55
	v_min_f32_e32 v17, v56, v57
	v_max_f32_e32 v56, v56, v57
	v_min_f32_e32 v48, v54, v56
	v_max_f32_e32 v54, v54, v56
	v_min_f32_e32 v37, v33, v17
	v_max_f32_e32 v33, v33, v17
	v_min_f32_e32 v30, v33, v48
	v_max_f32_e32 v33, v33, v48
	v_min_f32_e32 v46, v50, v54
	v_max_f32_e32 v50, v50, v54
	v_min_f32_e32 v19, v3, v30
	v_max_f32_e32 v3, v3, v30
	v_min_f32_e32 v39, v3, v46
	v_max_f32_e32 v3, v3, v46
	v_min_f32_e32 v15, v151, v33
	v_max_f32_e32 v151, v151, v33
	v_min_f32_e32 v0, v43, v37
	v_max_f32_e32 v43, v43, v37
	v_min_f32_e32 v35, v43, v15
	v_max_f32_e32 v43, v43, v15
	v_min_f32_e32 v12, v151, v3
	v_max_f32_e32 v151, v151, v3
	v_min_f32_e32 v47, v43, v39
	v_max_f32_e32 v43, v43, v39
	v_min_f32_e32 v28, v35, v19
	v_max_f32_e32 v35, v35, v19
	v_min_f32_e32 v49, v58, v59
	v_max_f32_e32 v58, v58, v59
	v_min_f32_e32 v44, v60, v61
	v_max_f32_e32 v60, v60, v61
	v_min_f32_e32 v51, v58, v60
	v_max_f32_e32 v58, v58, v60
	v_min_f32_e32 v53, v49, v44
	v_max_f32_e32 v49, v49, v44
	v_min_f32_e32 v52, v49, v51
	v_max_f32_e32 v49, v49, v51
	v_min_f32_e32 v45, v62, v63
	v_max_f32_e32 v62, v62, v63
	v_min_f32_e32 v31, v64, v65
	v_max_f32_e32 v64, v64, v65
	v_min_f32_e32 v55, v62, v64
	v_max_f32_e32 v62, v62, v64
	v_min_f32_e32 v57, v45, v31
	v_max_f32_e32 v45, v45, v31
	v_min_f32_e32 v56, v45, v55
	v_max_f32_e32 v45, v45, v55
	v_min_f32_e32 v17, v58, v62
	v_max_f32_e32 v58, v58, v62
	v_min_f32_e32 v48, v52, v56
	v_max_f32_e32 v52, v52, v56
	v_min_f32_e32 v54, v52, v17
	v_max_f32_e32 v52, v52, v17
	v_min_f32_e32 v30, v49, v45
	v_max_f32_e32 v49, v49, v45
	v_min_f32_e32 v46, v53, v57
	v_max_f32_e32 v53, v53, v57
	v_min_f32_e32 v33, v53, v30
	v_max_f32_e32 v53, v53, v30
	v_min_f32_e32 v37, v49, v52
	v_max_f32_e32 v49, v49, v52
; DI void ins16n(float (&t)[16], float x, int nf) {
; #pragma unroll
;   for (int i = 15; i >= 1; --i)
;     if (i <= nf) t[i] = __builtin_amdgcn_fmed3f(t[i - 1], t[i], x);
;   t[0] = fmaxf(t[0], x);
; }
; DI void phase_peer_q(const Params& p, int layer, u16* lds, const int WAVE_S) {
;     ...
; #pragma unroll
;       for (int i = 0; i < 16; ++i) t[i] = -3.0e38f;
; #pragma unroll
;       for (int nt = 0; nt < 4; ++nt)
; #pragma unroll
;         for (int i = 0; i < 16; ++i) {
;           const uint32_t n = nt * 32 + (i & 3) + 8 * (i >> 2) + 4 * h;
;           const float v = __uint_as_float((__float_as_uint(acc[nt][0][i]) & ~127u) | n);
;           ins16n(t, v, nt * 16 + i);
;         }
	v_min_f32_e32 v15, v53, v54
	v_max_f32_e32 v53, v53, v54
	v_min_f32_e32 v3, v33, v48
	v_max_f32_e32 v33, v33, v48
	v_min_f32_e32 v39, v50, v58
	v_max_f32_e32 v50, v50, v58
	v_min_f32_e32 v19, v47, v15
	v_max_f32_e32 v47, v47, v15
	v_min_f32_e32 v59, v47, v39
	v_max_f32_e32 v47, v47, v39
	v_min_f32_e32 v61, v12, v37
	v_max_f32_e32 v12, v12, v37
	v_min_f32_e32 v60, v28, v3
	v_max_f32_e32 v28, v28, v3
	v_min_f32_e32 v44, v28, v61
	v_max_f32_e32 v28, v28, v61
	v_min_f32_e32 v51, v12, v47
	v_max_f32_e32 v12, v12, v47
	v_min_f32_e32 v63, v28, v59
	v_max_f32_e32 v28, v28, v59
	v_min_f32_e32 v65, v44, v19
	v_max_f32_e32 v44, v44, v19
	v_min_f32_e32 v64, v151, v49
	v_max_f32_e32 v151, v151, v49
	v_min_f32_e32 v31, v35, v33
	v_max_f32_e32 v35, v35, v33
	v_min_f32_e32 v55, v35, v64
	v_max_f32_e32 v35, v35, v64
	v_min_f32_e32 v62, v43, v53
	v_max_f32_e32 v43, v43, v53
	v_min_f32_e32 v56, v0, v46
	v_max_f32_e32 v0, v0, v46
	v_min_f32_e32 v17, v0, v62
	v_max_f32_e32 v0, v0, v62
	v_min_f32_e32 v45, v43, v35
	v_max_f32_e32 v43, v43, v35
	v_min_f32_e32 v57, v0, v55
	v_max_f32_e32 v0, v0, v55
	v_min_f32_e32 v30, v17, v31
	v_max_f32_e32 v17, v17, v31
	v_min_f32_e32 v52, v151, v12
	v_max_f32_e32 v151, v151, v12
	v_min_f32_e32 v54, v43, v51
	v_max_f32_e32 v43, v43, v51
	v_min_f32_e32 v48, v45, v28
	v_max_f32_e32 v45, v45, v28
	v_min_f32_e32 v58, v0, v63
	v_max_f32_e32 v0, v0, v63
	v_min_f32_e32 v15, v57, v44
	v_max_f32_e32 v57, v57, v44
	v_min_f32_e32 v39, v17, v65
	v_max_f32_e32 v17, v17, v65
	v_min_f32_e32 v37, v30, v60
	v_max_f32_e32 v30, v30, v60
	v_max_f32_e32 v2, v2, v24
	v_max_f32_e32 v134, v134, v5
	v_max_f32_e32 v4, v4, v144
	v_max_f32_e32 v137, v137, v7
	v_max_f32_e32 v6, v6, v139
	v_max_f32_e32 v135, v135, v136
	v_max_f32_e32 v141, v141, v25
	v_max_f32_e32 v150, v150, v26
	v_max_f32_e32 v10, v10, v152
	v_max_f32_e32 v9, v9, v16
	v_max_f32_e32 v149, v149, v13
	v_max_f32_e32 v140, v140, v22
	v_max_f32_e32 v148, v148, v11
	v_max_f32_e32 v143, v143, v20
	v_max_f32_e32 v142, v142, v138
	v_max_f32_e32 v8, v8, v18
	v_min_f32_e32 v3, v2, v10
	v_max_f32_e32 v2, v2, v10
	v_min_f32_e32 v61, v134, v9
	v_max_f32_e32 v134, v134, v9
	v_min_f32_e32 v47, v4, v149
	v_max_f32_e32 v4, v4, v149
	v_min_f32_e32 v59, v137, v140
	v_max_f32_e32 v137, v137, v140
	v_min_f32_e32 v19, v6, v148
	v_max_f32_e32 v6, v6, v148
	v_min_f32_e32 v49, v135, v143
	v_max_f32_e32 v135, v135, v143
	v_min_f32_e32 v33, v141, v142
	v_max_f32_e32 v141, v141, v142
	v_min_f32_e32 v64, v150, v8
	v_max_f32_e32 v150, v150, v8
	v_min_f32_e32 v53, v2, v6
	v_max_f32_e32 v2, v2, v6
	v_min_f32_e32 v46, v134, v135
	v_max_f32_e32 v134, v134, v135
	v_min_f32_e32 v62, v4, v141
	v_max_f32_e32 v4, v4, v141
	v_min_f32_e32 v35, v137, v150
	v_max_f32_e32 v137, v137, v150
	v_min_f32_e32 v55, v3, v19
	v_max_f32_e32 v3, v3, v19
	v_min_f32_e32 v31, v61, v49
	v_max_f32_e32 v61, v61, v49
	v_min_f32_e32 v12, v47, v33
	v_max_f32_e32 v47, v47, v33
	v_min_f32_e32 v51, v59, v64
	v_max_f32_e32 v59, v59, v64
	v_min_f32_e32 v28, v2, v4
	v_max_f32_e32 v2, v2, v4
	v_min_f32_e32 v63, v134, v137
	v_max_f32_e32 v134, v134, v137
	v_min_f32_e32 v44, v53, v62
	v_max_f32_e32 v53, v53, v62
	v_min_f32_e32 v65, v46, v35
	v_max_f32_e32 v46, v46, v35
	v_min_f32_e32 v60, v3, v47
	v_max_f32_e32 v3, v3, v47
	v_min_f32_e32 v18, v61, v59
	v_max_f32_e32 v61, v61, v59
	v_min_f32_e32 v138, v55, v12
	v_max_f32_e32 v55, v55, v12
	v_min_f32_e32 v20, v31, v51
	v_max_f32_e32 v31, v31, v51
	v_min_f32_e32 v11, v2, v134
	v_max_f32_e32 v2, v2, v134
	v_min_f32_e32 v22, v28, v63
	v_max_f32_e32 v28, v28, v63
	v_min_f32_e32 v13, v53, v46
	v_max_f32_e32 v53, v53, v46
	v_min_f32_e32 v16, v44, v65
	v_max_f32_e32 v44, v44, v65
	v_min_f32_e32 v152, v3, v61
	v_max_f32_e32 v3, v3, v61
	v_min_f32_e32 v26, v60, v18
	v_max_f32_e32 v60, v60, v18
	v_min_f32_e32 v25, v55, v31
	v_max_f32_e32 v55, v55, v31
	v_min_f32_e32 v136, v138, v20
	v_max_f32_e32 v138, v138, v20
	v_max_f32_e32 v34, v34, v56
	v_max_f32_e32 v145, v145, v37
	v_max_f32_e32 v36, v36, v30
	v_max_f32_e32 v27, v27, v39
	v_max_f32_e32 v38, v38, v17
	v_max_f32_e32 v29, v29, v15
	v_max_f32_e32 v32, v32, v57
	v_max_f32_e32 v154, v154, v58
	v_max_f32_e32 v42, v42, v0
	v_max_f32_e32 v41, v41, v48
	v_max_f32_e32 v153, v153, v45
	v_max_f32_e32 v155, v155, v54
	v_max_f32_e32 v23, v23, v43
	v_max_f32_e32 v14, v14, v52
	v_max_f32_e32 v21, v21, v151
	v_max_f32_e32 v40, v40, v50
	v_min_f32_e32 v139, v34, v42
	v_max_f32_e32 v34, v34, v42
	v_min_f32_e32 v7, v145, v41
	v_max_f32_e32 v145, v145, v41
	v_min_f32_e32 v144, v36, v153
	v_max_f32_e32 v36, v36, v153
	v_min_f32_e32 v5, v27, v155
	v_max_f32_e32 v27, v27, v155
	v_min_f32_e32 v24, v38, v23
	v_max_f32_e32 v38, v38, v23
	v_min_f32_e32 v10, v29, v14
	v_max_f32_e32 v29, v29, v14
	v_min_f32_e32 v9, v32, v21
	v_max_f32_e32 v32, v32, v21
	v_min_f32_e32 v149, v154, v40
	v_max_f32_e32 v154, v154, v40
	v_min_f32_e32 v140, v34, v38
	v_max_f32_e32 v34, v34, v38
	v_min_f32_e32 v148, v145, v29
	v_max_f32_e32 v145, v145, v29
	v_min_f32_e32 v143, v36, v32
	v_max_f32_e32 v36, v36, v32
	v_min_f32_e32 v142, v27, v154
	v_max_f32_e32 v27, v27, v154
	v_min_f32_e32 v8, v139, v24
	v_max_f32_e32 v139, v139, v24
	v_min_f32_e32 v6, v7, v10
	v_max_f32_e32 v7, v7, v10
	v_min_f32_e32 v135, v144, v9
	v_max_f32_e32 v144, v144, v9
	v_min_f32_e32 v141, v5, v149
	v_max_f32_e32 v5, v5, v149
	v_min_f32_e32 v150, v34, v36
	v_max_f32_e32 v34, v34, v36
	v_min_f32_e32 v19, v145, v27
	v_max_f32_e32 v145, v145, v27
	v_min_f32_e32 v49, v140, v143
	v_max_f32_e32 v140, v140, v143
	v_min_f32_e32 v33, v148, v142
	v_max_f32_e32 v148, v148, v142
	v_min_f32_e32 v64, v139, v144
	v_max_f32_e32 v139, v139, v144
; DI void phase_peer_q(const Params& p, int layer, u16* lds, const int WAVE_S) {
;     ...
;       float o16[16];
; #pragma unroll
;       for (int i = 0; i < 16; ++i) {
;         auto rr = __builtin_amdgcn_permlane32_swap(__float_as_uint(t[i]), __float_as_uint(t[i]), false, false);
;         o16[i] = __uint_as_float(h ? rr[0] : rr[1]);
;       }
	v_min_f32_e32 v4, v7, v5
	v_max_f32_e32 v7, v7, v5
	v_min_f32_e32 v137, v8, v135
	v_max_f32_e32 v8, v8, v135
	v_min_f32_e32 v62, v6, v141
	v_max_f32_e32 v6, v6, v141
	v_min_f32_e32 v35, v34, v145
	v_max_f32_e32 v34, v34, v145
	v_min_f32_e32 v47, v150, v19
	v_max_f32_e32 v150, v150, v19
	v_min_f32_e32 v59, v140, v148
	v_max_f32_e32 v140, v140, v148
	v_min_f32_e32 v12, v49, v33
	v_max_f32_e32 v49, v49, v33
	v_min_f32_e32 v51, v139, v7
	v_max_f32_e32 v139, v139, v7
	v_min_f32_e32 v134, v64, v4
	v_max_f32_e32 v64, v64, v4
	v_min_f32_e32 v63, v8, v6
	v_max_f32_e32 v8, v8, v6
	v_min_f32_e32 v46, v137, v62
	v_max_f32_e32 v137, v137, v62
	v_max_f32_e32 v2, v2, v46
	v_max_f32_e32 v11, v11, v137
	v_max_f32_e32 v28, v28, v63
	v_max_f32_e32 v22, v22, v8
	v_max_f32_e32 v53, v53, v134
	v_max_f32_e32 v13, v13, v64
	v_max_f32_e32 v44, v44, v51
	v_max_f32_e32 v16, v16, v139
	v_max_f32_e32 v3, v3, v12
	v_max_f32_e32 v152, v152, v49
	v_max_f32_e32 v60, v60, v59
	v_max_f32_e32 v26, v26, v140
	v_max_f32_e32 v55, v55, v47
	v_max_f32_e32 v25, v25, v150
	v_max_f32_e32 v138, v138, v35
	v_max_f32_e32 v136, v136, v34
	v_min_f32_e32 v65, v2, v3
	v_max_f32_e32 v2, v2, v3
	v_min_f32_e32 v61, v11, v152
	v_max_f32_e32 v11, v11, v152
	v_min_f32_e32 v18, v28, v60
	v_max_f32_e32 v28, v28, v60
	v_min_f32_e32 v31, v22, v26
	v_max_f32_e32 v22, v22, v26
	v_min_f32_e32 v20, v53, v55
	v_max_f32_e32 v53, v53, v55
	v_min_f32_e32 v50, v13, v25
	v_max_f32_e32 v13, v13, v25
	v_min_f32_e32 v151, v44, v138
	v_max_f32_e32 v44, v44, v138
	v_min_f32_e32 v52, v16, v136
	v_max_f32_e32 v16, v16, v136
	v_min_f32_e32 v43, v2, v53
	v_max_f32_e32 v2, v2, v53
	v_min_f32_e32 v54, v11, v13
	v_max_f32_e32 v11, v11, v13
	v_min_f32_e32 v45, v28, v44
	v_max_f32_e32 v28, v28, v44
	v_min_f32_e32 v48, v22, v16
	v_max_f32_e32 v22, v22, v16
	v_min_f32_e32 v0, v65, v20
	v_max_f32_e32 v65, v65, v20
	v_min_f32_e32 v58, v61, v50
	v_max_f32_e32 v61, v61, v50
	v_min_f32_e32 v57, v18, v151
	v_max_f32_e32 v18, v18, v151
	v_min_f32_e32 v15, v31, v52
	v_max_f32_e32 v31, v31, v52
	v_min_f32_e32 v17, v2, v28
	v_max_f32_e32 v2, v2, v28
	v_min_f32_e32 v39, v11, v22
	v_max_f32_e32 v11, v11, v22
	v_min_f32_e32 v30, v43, v45
	v_max_f32_e32 v43, v43, v45
	v_min_f32_e32 v37, v54, v48
	v_max_f32_e32 v54, v54, v48
	v_min_f32_e32 v56, v65, v18
	v_max_f32_e32 v65, v65, v18
	v_min_f32_e32 v42, v61, v31
	v_max_f32_e32 v61, v61, v31
	v_min_f32_e32 v41, v0, v57
	v_max_f32_e32 v0, v0, v57
	v_min_f32_e32 v153, v58, v15
	v_max_f32_e32 v58, v58, v15
	v_min_f32_e32 v155, v2, v11
	v_max_f32_e32 v2, v2, v11
	v_min_f32_e32 v23, v17, v39
	v_max_f32_e32 v17, v17, v39
	v_min_f32_e32 v14, v43, v54
	v_max_f32_e32 v43, v43, v54
	v_min_f32_e32 v21, v30, v37
	v_max_f32_e32 v30, v30, v37
	v_min_f32_e32 v40, v65, v61
	v_max_f32_e32 v65, v65, v61
	v_min_f32_e32 v38, v56, v42
	v_max_f32_e32 v56, v56, v42
	v_min_f32_e32 v29, v0, v58
	v_max_f32_e32 v0, v0, v58
	v_min_f32_e32 v32, v41, v153
	v_max_f32_e32 v41, v41, v153
	v_mov_b32_e32 v16, v17
	v_mov_b32_e32 v15, v23
	v_mov_b32_e32 v13, v14
	v_mov_b32_e32 v12, v30
	v_mov_b32_e32 v11, v21
	v_mov_b32_e32 v10, v65
	v_mov_b32_e32 v9, v40
	v_mov_b32_e32 v8, v56
	v_mov_b32_e32 v7, v38
	v_mov_b32_e32 v6, v0
	v_mov_b32_e32 v5, v29
	v_mov_b32_e32 v4, v41
	v_mov_b32_e32 v3, v32
	v_mov_b32_e32 v0, v2
	v_mov_b32_e32 v17, v155
	v_mov_b32_e32 v14, v43
	v_mov_b32_e32 v2, v0
	v_mov_b32_e32 v18, v0
	s_nop 1
	v_permlane32_swap_b32_e32 v2, v18
	v_cndmask_b32_e64 v2, v2, v18, s[34:35]
	v_mov_b32_e32 v18, v17
	v_mov_b32_e32 v19, v17
	s_nop 1
	v_permlane32_swap_b32_e32 v18, v19
	v_cndmask_b32_e64 v18, v18, v19, s[34:35]
	v_mov_b32_e32 v19, v16
	v_mov_b32_e32 v20, v16
	s_nop 1
	v_permlane32_swap_b32_e32 v19, v20
	v_cndmask_b32_e64 v19, v19, v20, s[34:35]
	v_mov_b32_e32 v20, v15
	v_mov_b32_e32 v21, v15
	s_nop 1
	v_permlane32_swap_b32_e32 v20, v21
	v_cndmask_b32_e64 v20, v20, v21, s[34:35]
	v_mov_b32_e32 v21, v14
	v_mov_b32_e32 v22, v14
	s_nop 1
	v_permlane32_swap_b32_e32 v21, v22
	v_cndmask_b32_e64 v21, v21, v22, s[34:35]
	v_mov_b32_e32 v22, v13
; DI void phase_peer_q(const Params& p, int layer, u16* lds, const int WAVE_S) {
;     ...
;       float o16[16];
; #pragma unroll
;       for (int i = 0; i < 16; ++i) {
;         auto rr = __builtin_amdgcn_permlane32_swap(__float_as_uint(t[i]), __float_as_uint(t[i]), false, false);
;         o16[i] = __uint_as_float(h ? rr[0] : rr[1]);
;       }
; #pragma unroll
;       for (int i = 0; i < 16; ++i) ins16(t, o16[i]);
;       if (half == 0) {
; #pragma unroll
;         for (int i = 0; i < 16; ++i) t0[i] = t[i];
;       }
;     }
	v_mov_b32_e32 v23, v13
	s_nop 1
	v_permlane32_swap_b32_e32 v22, v23
	v_cndmask_b32_e64 v22, v22, v23, s[34:35]
	v_mov_b32_e32 v23, v12
	v_mov_b32_e32 v24, v12
	s_nop 1
	v_permlane32_swap_b32_e32 v23, v24
	v_cndmask_b32_e64 v23, v23, v24, s[34:35]
	v_mov_b32_e32 v24, v11
	v_mov_b32_e32 v25, v11
	s_nop 1
	v_permlane32_swap_b32_e32 v24, v25
	v_cndmask_b32_e64 v24, v24, v25, s[34:35]
	v_mov_b32_e32 v25, v10
	v_mov_b32_e32 v26, v10
	s_nop 1
	v_permlane32_swap_b32_e32 v25, v26
	v_cndmask_b32_e64 v25, v25, v26, s[34:35]
	v_mov_b32_e32 v26, v9
	v_mov_b32_e32 v27, v9
	s_nop 1
	v_permlane32_swap_b32_e32 v26, v27
	v_cndmask_b32_e64 v26, v26, v27, s[34:35]
	v_mov_b32_e32 v27, v8
	v_mov_b32_e32 v28, v8
	s_nop 1
	v_permlane32_swap_b32_e32 v27, v28
	v_cndmask_b32_e64 v27, v27, v28, s[34:35]
	v_mov_b32_e32 v28, v7
	v_mov_b32_e32 v29, v7
	s_nop 1
	v_permlane32_swap_b32_e32 v28, v29
	v_cndmask_b32_e64 v28, v28, v29, s[34:35]
	v_mov_b32_e32 v29, v6
	v_mov_b32_e32 v30, v6
	s_nop 1
	v_permlane32_swap_b32_e32 v29, v30
	v_cndmask_b32_e64 v29, v29, v30, s[34:35]
	v_mov_b32_e32 v30, v5
	v_mov_b32_e32 v31, v5
	s_nop 1
	v_permlane32_swap_b32_e32 v30, v31
	v_cndmask_b32_e64 v30, v30, v31, s[34:35]
	v_mov_b32_e32 v31, v4
	v_mov_b32_e32 v32, v4
	s_nop 1
	v_permlane32_swap_b32_e32 v31, v32
	v_cndmask_b32_e64 v31, v31, v32, s[34:35]
	v_mov_b32_e32 v32, v3
	v_mov_b32_e32 v33, v3
	s_nop 1
	v_permlane32_swap_b32_e32 v32, v33
	v_cndmask_b32_e64 v32, v32, v33, s[34:35]
	v_max_f32_e32 v0, v0, v32
	v_max_f32_e32 v17, v17, v31
	v_max_f32_e32 v16, v16, v30
	v_max_f32_e32 v15, v15, v29
	v_max_f32_e32 v14, v14, v28
	v_max_f32_e32 v13, v13, v27
	v_max_f32_e32 v12, v12, v26
	v_max_f32_e32 v11, v11, v25
	v_max_f32_e32 v10, v10, v24
	v_max_f32_e32 v9, v9, v23
	v_max_f32_e32 v8, v8, v22
	v_max_f32_e32 v7, v7, v21
	v_max_f32_e32 v6, v6, v20
	v_max_f32_e32 v5, v5, v19
	v_max_f32_e32 v4, v4, v18
	v_max_f32_e32 v3, v3, v2
	v_min_f32_e32 v25, v0, v10
	v_max_f32_e32 v2, v0, v10
	v_min_f32_e32 v26, v17, v9
	v_max_f32_e32 v18, v17, v9
	v_min_f32_e32 v27, v16, v8
	v_max_f32_e32 v19, v16, v8
	v_min_f32_e32 v28, v15, v7
	v_max_f32_e32 v20, v15, v7
	v_min_f32_e32 v29, v14, v6
	v_max_f32_e32 v21, v14, v6
	v_min_f32_e32 v30, v13, v5
	v_max_f32_e32 v22, v13, v5
	v_min_f32_e32 v31, v12, v4
	v_max_f32_e32 v23, v12, v4
	v_min_f32_e32 v32, v11, v3
	v_max_f32_e32 v24, v11, v3
	v_min_f32_e32 v14, v2, v21
	v_max_f32_e32 v0, v2, v21
	v_min_f32_e32 v13, v18, v22
	v_max_f32_e32 v17, v18, v22
	v_min_f32_e32 v12, v19, v23
	v_max_f32_e32 v16, v19, v23
	v_min_f32_e32 v11, v20, v24
	v_max_f32_e32 v15, v20, v24
	v_min_f32_e32 v6, v25, v29
	v_max_f32_e32 v10, v25, v29
	v_min_f32_e32 v5, v26, v30
	v_max_f32_e32 v9, v26, v30
	v_min_f32_e32 v4, v27, v31
	v_max_f32_e32 v8, v27, v31
	v_min_f32_e32 v3, v28, v32
	v_max_f32_e32 v7, v28, v32
	v_min_f32_e32 v19, v0, v16
	v_max_f32_e32 v2, v0, v16
	v_min_f32_e32 v20, v17, v15
	v_max_f32_e32 v18, v17, v15
	v_min_f32_e32 v23, v14, v12
	v_max_f32_e32 v21, v14, v12
	v_min_f32_e32 v24, v13, v11
	v_max_f32_e32 v22, v13, v11
	v_min_f32_e32 v27, v10, v8
	v_max_f32_e32 v25, v10, v8
	v_min_f32_e32 v28, v9, v7
	v_max_f32_e32 v26, v9, v7
	v_min_f32_e32 v31, v6, v4
	v_max_f32_e32 v29, v6, v4
	v_min_f32_e32 v32, v5, v3
	v_max_f32_e32 v30, v5, v3
	v_min_f32_e32 v3, v2, v18
	v_max_f32_e32 v2, v2, v18
	v_min_f32_e32 v5, v19, v20
	v_max_f32_e32 v4, v19, v20
	v_min_f32_e32 v7, v21, v22
	v_max_f32_e32 v6, v21, v22
	v_min_f32_e32 v9, v23, v24
	v_max_f32_e32 v8, v23, v24
	v_min_f32_e32 v17, v25, v26
	v_max_f32_e32 v16, v25, v26
	v_min_f32_e32 v15, v27, v28
	v_max_f32_e32 v14, v27, v28
	v_min_f32_e32 v13, v29, v30
	v_max_f32_e32 v12, v29, v30
	v_min_f32_e32 v11, v31, v32
	v_max_f32_e32 v10, v31, v32
	s_cbranch_vccz .LBB0_388
	v_mov_b64_e32 v[18:19], v[98:99]
	v_mov_b64_e32 v[20:21], v[100:101]
	v_mov_b64_e32 v[22:23], v[102:103]
	v_mov_b64_e32 v[24:25], v[104:105]
	v_mov_b64_e32 v[26:27], v[106:107]
	v_mov_b64_e32 v[28:29], v[108:109]
	v_mov_b64_e32 v[30:31], v[110:111]
	v_mov_b64_e32 v[32:33], v[112:113]
	s_branch .LBB0_389
